# LayerNorm phases walk the rows in descending order (most recently written GEMM output first)
# speedup vs baseline: 1.0073x; 1.0073x over previous
.LBB0_790:
	s_cmp_lt_i32 s28, 8
	s_cselect_b64 s[0:1], -1, 0
	s_cmp_gt_i32 s29, 7
	s_cselect_b64 s[2:3], -1, 0
	s_and_b64 s[0:1], s[0:1], s[2:3]
	s_andn2_b64 vcc, exec, s[0:1]
	s_cbranch_vccnz .LBB0_856
	s_mov_b64 s[8:9], exec
	v_readlane_b32 s0, v254, 4
	v_lshrrev_b32_e32 v0, 6, v200
	s_lshl_b32 s3, s30, 3
	v_readfirstlane_b32 s2, v0
	v_mbcnt_lo_u32_b32 v0, -1, 0
	v_mbcnt_hi_u32_b32 v0, -1, v0
	s_add_i32 s2, s2, s0
	s_cmp_ge_i32 s2, 0x10000
	s_cbranch_scc1 .Llna1_done
	v_lshlrev_b32_e32 v1, 3, v0
	v_lshlrev_b32_e32 v0, 4, v0
	s_add_u32 s4, s36, 0
	s_addc_u32 s5, s37, 0
	s_add_u32 s6, s38, 0
	s_addc_u32 s7, s39, 0
	global_load_dwordx4 v[80:83], v0, s[4:5] offset:0
	global_load_dwordx4 v[84:87], v0, s[4:5] offset:1024
	global_load_dwordx4 v[88:91], v0, s[4:5] offset:2048
	global_load_dwordx4 v[92:95], v0, s[4:5] offset:3072
	global_load_dwordx4 v[96:99], v0, s[6:7] offset:0
	global_load_dwordx4 v[100:103], v0, s[6:7] offset:1024
	global_load_dwordx4 v[104:107], v0, s[6:7] offset:2048
	global_load_dwordx4 v[108:111], v0, s[6:7] offset:3072
	s_add_u32 s10, s26, 0x6000000
	s_addc_u32 s11, s27, 0
	v_mov_b32_e32 v112, 0x3727c5ac
	s_add_i32 s12, s2, s3
	s_cmp_lt_i32 s12, 0x10000
	s_cselect_b32 s13, s12, s2
	s_sub_i32 s4, 0xffff, s2
	s_lshl_b32 s4, s4, 12
	s_add_u32 s4, s24, s4
	s_addc_u32 s5, s25, 0
	s_sub_i32 s6, 0xffff, s13
	s_lshl_b32 s6, s6, 12
	s_add_u32 s6, s24, s6
	s_addc_u32 s7, s25, 0
	global_load_dwordx4 v[48:51], v0, s[4:5] offset:0
	global_load_dwordx4 v[52:55], v0, s[4:5] offset:1024
	global_load_dwordx4 v[56:59], v0, s[4:5] offset:2048
	global_load_dwordx4 v[60:63], v0, s[4:5] offset:3072
	global_load_dwordx4 v[64:67], v0, s[6:7] offset:0
	global_load_dwordx4 v[68:71], v0, s[6:7] offset:1024
	global_load_dwordx4 v[72:75], v0, s[6:7] offset:2048
	global_load_dwordx4 v[76:79], v0, s[6:7] offset:3072
	s_waitcnt vmcnt(0)
	s_branch .Llna1_enter

.Llna1_enter:
	s_mov_b32 s8, s2
	s_add_i32 s9, s2, s3
	v_mov_b64_e32 v[16:17], v[48:49]
	v_mov_b64_e32 v[18:19], v[50:51]
	v_mov_b64_e32 v[20:21], v[52:53]
	v_mov_b64_e32 v[22:23], v[54:55]
	v_mov_b64_e32 v[24:25], v[56:57]
	v_mov_b64_e32 v[26:27], v[58:59]
	v_mov_b64_e32 v[28:29], v[60:61]
	v_mov_b64_e32 v[30:31], v[62:63]
	v_mov_b64_e32 v[32:33], v[64:65]
	v_mov_b64_e32 v[34:35], v[66:67]
	v_mov_b64_e32 v[36:37], v[68:69]
	v_mov_b64_e32 v[38:39], v[70:71]
	v_mov_b64_e32 v[40:41], v[72:73]
	v_mov_b64_e32 v[42:43], v[74:75]
	v_mov_b64_e32 v[44:45], v[76:77]
	v_mov_b64_e32 v[46:47], v[78:79]
	s_lshl_b32 s12, s3, 1
	s_add_i32 s2, s2, s12
	s_cmp_ge_i32 s2, 0x10000
	s_cbranch_scc1 .Llna1_nopf
	s_add_i32 s12, s2, s3
	s_cmp_lt_i32 s12, 0x10000
	s_cselect_b32 s13, s12, s2
	s_sub_i32 s4, 0xffff, s2
	s_lshl_b32 s4, s4, 12
	s_add_u32 s4, s24, s4
	s_addc_u32 s5, s25, 0
	s_sub_i32 s6, 0xffff, s13
	s_lshl_b32 s6, s6, 12
	s_add_u32 s6, s24, s6
	s_addc_u32 s7, s25, 0
	global_load_dwordx4 v[48:51], v0, s[4:5] offset:0
	global_load_dwordx4 v[52:55], v0, s[4:5] offset:1024
	global_load_dwordx4 v[56:59], v0, s[4:5] offset:2048
	global_load_dwordx4 v[60:63], v0, s[4:5] offset:3072
	global_load_dwordx4 v[64:67], v0, s[6:7] offset:0
	global_load_dwordx4 v[68:71], v0, s[6:7] offset:1024
	global_load_dwordx4 v[72:75], v0, s[6:7] offset:2048
	global_load_dwordx4 v[76:79], v0, s[6:7] offset:3072
.Llna1_nopf:
	v_add_f32_e32 v113, v16, v20
	v_add_f32_e32 v114, v17, v21
	v_add_f32_e32 v115, v18, v22
	v_add_f32_e32 v116, v19, v23
	v_add_f32_e32 v117, v32, v36
	v_add_f32_e32 v118, v33, v37
	v_add_f32_e32 v119, v34, v38
	v_add_f32_e32 v120, v35, v39
	v_add_f32_e32 v113, v113, v24
	v_add_f32_e32 v113, v113, v28
	v_add_f32_e32 v114, v114, v25
	v_add_f32_e32 v114, v114, v29
	v_add_f32_e32 v115, v115, v26
	v_add_f32_e32 v115, v115, v30
	v_add_f32_e32 v116, v116, v27
	v_add_f32_e32 v116, v116, v31
	v_add_f32_e32 v117, v117, v40
	v_add_f32_e32 v117, v117, v44
	v_add_f32_e32 v118, v118, v41
	v_add_f32_e32 v118, v118, v45
	v_add_f32_e32 v119, v119, v42
	v_add_f32_e32 v119, v119, v46
	v_add_f32_e32 v120, v120, v43
	v_add_f32_e32 v120, v120, v47
	v_add_f32_e32 v113, v113, v114
	v_add_f32_e32 v115, v115, v116
	v_add_f32_e32 v117, v117, v118
	v_add_f32_e32 v119, v119, v120
	v_add_f32_e32 v113, v113, v115
	v_add_f32_e32 v117, v117, v119
	s_nop 1
	v_add_f32_dpp v113, v113, v113 quad_perm:[1,0,3,2] row_mask:0xf bank_mask:0xf
	v_add_f32_dpp v117, v117, v117 quad_perm:[1,0,3,2] row_mask:0xf bank_mask:0xf
	s_nop 1
	v_add_f32_dpp v113, v113, v113 quad_perm:[2,3,0,1] row_mask:0xf bank_mask:0xf
	v_add_f32_dpp v117, v117, v117 quad_perm:[2,3,0,1] row_mask:0xf bank_mask:0xf
	s_nop 1
	v_add_f32_dpp v113, v113, v113 row_half_mirror row_mask:0xf bank_mask:0xf
	v_add_f32_dpp v117, v117, v117 row_half_mirror row_mask:0xf bank_mask:0xf
	s_nop 1
	v_add_f32_dpp v113, v113, v113 row_mirror row_mask:0xf bank_mask:0xf
	v_add_f32_dpp v117, v117, v117 row_mirror row_mask:0xf bank_mask:0xf
	s_nop 1
	v_readlane_b32 s4, v113, 0
	v_readlane_b32 s5, v113, 16
	v_readlane_b32 s6, v113, 32
	v_readlane_b32 s7, v113, 48
	v_readlane_b32 s12, v117, 0
	v_readlane_b32 s13, v117, 16
	v_readlane_b32 s0, v117, 32
	v_readlane_b32 s1, v117, 48
	s_nop 1
	v_mov_b32_e32 v113, s4
	v_mov_b32_e32 v117, s12
	v_add_f32_e32 v113, s5, v113
	v_add_f32_e32 v117, s13, v117
	v_add_f32_e32 v113, s6, v113
	v_add_f32_e32 v117, s0, v117
	v_add_f32_e32 v113, s7, v113
	v_add_f32_e32 v117, s1, v117
	v_fmamk_f32 v16, v113, 0xba800000, v16
	v_fmamk_f32 v17, v113, 0xba800000, v17
	v_fmamk_f32 v18, v113, 0xba800000, v18
	v_fmamk_f32 v19, v113, 0xba800000, v19
	v_fmamk_f32 v20, v113, 0xba800000, v20
	v_fmamk_f32 v21, v113, 0xba800000, v21
	v_fmamk_f32 v22, v113, 0xba800000, v22
	v_fmamk_f32 v23, v113, 0xba800000, v23
	v_fmamk_f32 v24, v113, 0xba800000, v24
	v_fmamk_f32 v25, v113, 0xba800000, v25
	v_fmamk_f32 v26, v113, 0xba800000, v26
	v_fmamk_f32 v27, v113, 0xba800000, v27
	v_fmamk_f32 v28, v113, 0xba800000, v28
	v_fmamk_f32 v29, v113, 0xba800000, v29
	v_fmamk_f32 v30, v113, 0xba800000, v30
	v_fmamk_f32 v31, v113, 0xba800000, v31
	v_fmamk_f32 v32, v117, 0xba800000, v32
	v_fmamk_f32 v33, v117, 0xba800000, v33
	v_fmamk_f32 v34, v117, 0xba800000, v34
	v_fmamk_f32 v35, v117, 0xba800000, v35
	v_fmamk_f32 v36, v117, 0xba800000, v36
	v_fmamk_f32 v37, v117, 0xba800000, v37
	v_fmamk_f32 v38, v117, 0xba800000, v38
	v_fmamk_f32 v39, v117, 0xba800000, v39
	v_fmamk_f32 v40, v117, 0xba800000, v40
	v_fmamk_f32 v41, v117, 0xba800000, v41
	v_fmamk_f32 v42, v117, 0xba800000, v42
	v_fmamk_f32 v43, v117, 0xba800000, v43
	v_fmamk_f32 v44, v117, 0xba800000, v44
	v_fmamk_f32 v45, v117, 0xba800000, v45
	v_fmamk_f32 v46, v117, 0xba800000, v46
	v_fmamk_f32 v47, v117, 0xba800000, v47
	v_mul_f32_e32 v113, v16, v16
	v_mul_f32_e32 v114, v17, v17
	v_mul_f32_e32 v115, v18, v18
	v_mul_f32_e32 v116, v19, v19
	v_mul_f32_e32 v117, v32, v32
	v_mul_f32_e32 v118, v33, v33
	v_mul_f32_e32 v119, v34, v34
	v_mul_f32_e32 v120, v35, v35
	v_fmac_f32_e32 v113, v20, v20
	v_fmac_f32_e32 v113, v24, v24
	v_fmac_f32_e32 v113, v28, v28
	v_fmac_f32_e32 v114, v21, v21
	v_fmac_f32_e32 v114, v25, v25
	v_fmac_f32_e32 v114, v29, v29
	v_fmac_f32_e32 v115, v22, v22
	v_fmac_f32_e32 v115, v26, v26
	v_fmac_f32_e32 v115, v30, v30
	v_fmac_f32_e32 v116, v23, v23
	v_fmac_f32_e32 v116, v27, v27
	v_fmac_f32_e32 v116, v31, v31
	v_fmac_f32_e32 v117, v36, v36
	v_fmac_f32_e32 v117, v40, v40
	v_fmac_f32_e32 v117, v44, v44
	v_fmac_f32_e32 v118, v37, v37
	v_fmac_f32_e32 v118, v41, v41
	v_fmac_f32_e32 v118, v45, v45
	v_fmac_f32_e32 v119, v38, v38
	v_fmac_f32_e32 v119, v42, v42
	v_fmac_f32_e32 v119, v46, v46
	v_fmac_f32_e32 v120, v39, v39
	v_fmac_f32_e32 v120, v43, v43
	v_fmac_f32_e32 v120, v47, v47
	v_add_f32_e32 v113, v113, v114
	v_add_f32_e32 v115, v115, v116
	v_add_f32_e32 v117, v117, v118
	v_add_f32_e32 v119, v119, v120
	v_add_f32_e32 v113, v113, v115
	v_add_f32_e32 v117, v117, v119
	s_nop 1
	v_add_f32_dpp v113, v113, v113 quad_perm:[1,0,3,2] row_mask:0xf bank_mask:0xf
	v_add_f32_dpp v117, v117, v117 quad_perm:[1,0,3,2] row_mask:0xf bank_mask:0xf
	s_nop 1
	v_add_f32_dpp v113, v113, v113 quad_perm:[2,3,0,1] row_mask:0xf bank_mask:0xf
	v_add_f32_dpp v117, v117, v117 quad_perm:[2,3,0,1] row_mask:0xf bank_mask:0xf
	s_nop 1
	v_add_f32_dpp v113, v113, v113 row_half_mirror row_mask:0xf bank_mask:0xf
	v_add_f32_dpp v117, v117, v117 row_half_mirror row_mask:0xf bank_mask:0xf
	s_nop 1
	v_add_f32_dpp v113, v113, v113 row_mirror row_mask:0xf bank_mask:0xf
	v_add_f32_dpp v117, v117, v117 row_mirror row_mask:0xf bank_mask:0xf
	s_nop 1
	v_readlane_b32 s4, v113, 0
	v_readlane_b32 s5, v113, 16
	v_readlane_b32 s6, v113, 32
	v_readlane_b32 s7, v113, 48
	v_readlane_b32 s12, v117, 0
	v_readlane_b32 s13, v117, 16
	v_readlane_b32 s0, v117, 32
	v_readlane_b32 s1, v117, 48
	s_nop 1
	v_mov_b32_e32 v113, s4
	v_mov_b32_e32 v117, s12
	v_add_f32_e32 v113, s5, v113
	v_add_f32_e32 v117, s13, v117
	v_add_f32_e32 v113, s6, v113
	v_add_f32_e32 v117, s0, v117
	v_add_f32_e32 v113, s7, v113
	v_add_f32_e32 v117, s1, v117
	v_fmamk_f32 v113, v113, 0x3a800000, v112
	v_fmamk_f32 v117, v117, 0x3a800000, v112
	v_rsq_f32_e32 v113, v113
	v_rsq_f32_e32 v117, v117
	s_nop 0
	v_mul_f32_e32 v16, v16, v113
	v_mul_f32_e32 v17, v17, v113
	v_mul_f32_e32 v18, v18, v113
	v_mul_f32_e32 v19, v19, v113
	v_mul_f32_e32 v20, v20, v113
	v_mul_f32_e32 v21, v21, v113
	v_mul_f32_e32 v22, v22, v113
	v_mul_f32_e32 v23, v23, v113
	v_mul_f32_e32 v24, v24, v113
	v_mul_f32_e32 v25, v25, v113
	v_mul_f32_e32 v26, v26, v113
	v_mul_f32_e32 v27, v27, v113
	v_mul_f32_e32 v28, v28, v113
	v_mul_f32_e32 v29, v29, v113
	v_mul_f32_e32 v30, v30, v113
	v_mul_f32_e32 v31, v31, v113
	v_fma_f32 v16, v16, v80, v96
	v_fma_f32 v17, v17, v81, v97
	v_fma_f32 v18, v18, v82, v98
	v_fma_f32 v19, v19, v83, v99
	v_fma_f32 v20, v20, v84, v100
	v_fma_f32 v21, v21, v85, v101
	v_fma_f32 v22, v22, v86, v102
	v_fma_f32 v23, v23, v87, v103
	v_fma_f32 v24, v24, v88, v104
	v_fma_f32 v25, v25, v89, v105
	v_fma_f32 v26, v26, v90, v106
	v_fma_f32 v27, v27, v91, v107
	v_fma_f32 v28, v28, v92, v108
	v_fma_f32 v29, v29, v93, v109
	v_fma_f32 v30, v30, v94, v110
	v_fma_f32 v31, v31, v95, v111
	v_mul_f32_e32 v32, v32, v117
	v_mul_f32_e32 v33, v33, v117
	v_mul_f32_e32 v34, v34, v117
	v_mul_f32_e32 v35, v35, v117
	v_mul_f32_e32 v36, v36, v117
	v_mul_f32_e32 v37, v37, v117
	v_mul_f32_e32 v38, v38, v117
	v_mul_f32_e32 v39, v39, v117
	v_mul_f32_e32 v40, v40, v117
	v_mul_f32_e32 v41, v41, v117
	v_mul_f32_e32 v42, v42, v117
	v_mul_f32_e32 v43, v43, v117
	v_mul_f32_e32 v44, v44, v117
	v_mul_f32_e32 v45, v45, v117
	v_mul_f32_e32 v46, v46, v117
	v_mul_f32_e32 v47, v47, v117
	v_fma_f32 v32, v32, v80, v96
	v_fma_f32 v33, v33, v81, v97
	v_fma_f32 v34, v34, v82, v98
	v_fma_f32 v35, v35, v83, v99
	v_fma_f32 v36, v36, v84, v100
	v_fma_f32 v37, v37, v85, v101
	v_fma_f32 v38, v38, v86, v102
	v_fma_f32 v39, v39, v87, v103
	v_fma_f32 v40, v40, v88, v104
	v_fma_f32 v41, v41, v89, v105
	v_fma_f32 v42, v42, v90, v106
	v_fma_f32 v43, v43, v91, v107
	v_fma_f32 v44, v44, v92, v108
	v_fma_f32 v45, v45, v93, v109
	v_fma_f32 v46, v46, v94, v110
	v_fma_f32 v47, v47, v95, v111
	v_cvt_pk_bf16_f32 v16, v16, v17
	v_cvt_pk_bf16_f32 v17, v18, v19
	v_cvt_pk_bf16_f32 v18, v20, v21
	v_cvt_pk_bf16_f32 v19, v22, v23
	v_cvt_pk_bf16_f32 v20, v24, v25
	v_cvt_pk_bf16_f32 v21, v26, v27
	v_cvt_pk_bf16_f32 v22, v28, v29
	v_cvt_pk_bf16_f32 v23, v30, v31
	v_cvt_pk_bf16_f32 v32, v32, v33
	v_cvt_pk_bf16_f32 v33, v34, v35
	v_cvt_pk_bf16_f32 v34, v36, v37
	v_cvt_pk_bf16_f32 v35, v38, v39
	v_cvt_pk_bf16_f32 v36, v40, v41
	v_cvt_pk_bf16_f32 v37, v42, v43
	v_cvt_pk_bf16_f32 v38, v44, v45
	v_cvt_pk_bf16_f32 v39, v46, v47
	s_sub_i32 s4, 0xffff, s8
	s_lshl_b32 s4, s4, 11
	s_add_u32 s4, s10, s4
	s_addc_u32 s5, s11, 0
	global_store_dwordx2 v1, v[16:17], s[4:5] offset:0
	global_store_dwordx2 v1, v[18:19], s[4:5] offset:512
	global_store_dwordx2 v1, v[20:21], s[4:5] offset:1024
	global_store_dwordx2 v1, v[22:23], s[4:5] offset:1536
	s_cmp_ge_i32 s9, 0x10000
	s_cbranch_scc1 .Llna1_st1
	s_sub_i32 s6, 0xffff, s9
	s_lshl_b32 s6, s6, 11
	s_add_u32 s6, s10, s6
	s_addc_u32 s7, s11, 0
	global_store_dwordx2 v1, v[32:33], s[6:7] offset:0
	global_store_dwordx2 v1, v[34:35], s[6:7] offset:512
	global_store_dwordx2 v1, v[36:37], s[6:7] offset:1024
	global_store_dwordx2 v1, v[38:39], s[6:7] offset:1536

.LBB0_1079:
	s_cmp_lt_i32 s28, 12
	s_cselect_b64 s[0:1], -1, 0
	s_cmp_gt_i32 s29, 11
	s_cselect_b64 s[2:3], -1, 0
	s_and_b64 s[0:1], s[0:1], s[2:3]
	s_andn2_b64 vcc, exec, s[0:1]
	s_cbranch_vccnz .LBB0_1145
	s_mov_b64 s[8:9], exec
	v_readlane_b32 s0, v254, 4
	v_lshrrev_b32_e32 v0, 6, v200
	s_lshl_b32 s3, s30, 3
	v_readfirstlane_b32 s2, v0
	v_mbcnt_lo_u32_b32 v0, -1, 0
	v_mbcnt_hi_u32_b32 v0, -1, v0
	s_add_i32 s2, s2, s0
	s_cmp_ge_i32 s2, 0x10000
	s_cbranch_scc1 .Llna2_done
	v_lshlrev_b32_e32 v1, 3, v0
	v_lshlrev_b32_e32 v0, 4, v0
	s_add_u32 s4, s40, 0
	s_addc_u32 s5, s41, 0
	s_add_u32 s6, s42, 0
	s_addc_u32 s7, s43, 0
	global_load_dwordx4 v[80:83], v0, s[4:5] offset:0
	global_load_dwordx4 v[84:87], v0, s[4:5] offset:1024
	global_load_dwordx4 v[88:91], v0, s[4:5] offset:2048
	global_load_dwordx4 v[92:95], v0, s[4:5] offset:3072
	global_load_dwordx4 v[96:99], v0, s[6:7] offset:0
	global_load_dwordx4 v[100:103], v0, s[6:7] offset:1024
	global_load_dwordx4 v[104:107], v0, s[6:7] offset:2048
	global_load_dwordx4 v[108:111], v0, s[6:7] offset:3072
	s_add_u32 s10, s26, 0x6000000
	s_addc_u32 s11, s27, 0
	v_mov_b32_e32 v112, 0x3727c5ac
	s_add_i32 s12, s2, s3
	s_cmp_lt_i32 s12, 0x10000
	s_cselect_b32 s13, s12, s2
	s_sub_i32 s4, 0xffff, s2
	s_lshl_b32 s4, s4, 12
	s_add_u32 s4, s24, s4
	s_addc_u32 s5, s25, 0
	s_sub_i32 s6, 0xffff, s13
	s_lshl_b32 s6, s6, 12
	s_add_u32 s6, s24, s6
	s_addc_u32 s7, s25, 0
	global_load_dwordx4 v[48:51], v0, s[4:5] offset:0
	global_load_dwordx4 v[52:55], v0, s[4:5] offset:1024
	global_load_dwordx4 v[56:59], v0, s[4:5] offset:2048
	global_load_dwordx4 v[60:63], v0, s[4:5] offset:3072
	global_load_dwordx4 v[64:67], v0, s[6:7] offset:0
	global_load_dwordx4 v[68:71], v0, s[6:7] offset:1024
	global_load_dwordx4 v[72:75], v0, s[6:7] offset:2048
	global_load_dwordx4 v[76:79], v0, s[6:7] offset:3072
	s_waitcnt vmcnt(0)
	s_branch .Llna2_enter

.LBB0_1476:
	s_cmp_lt_i32 s28, 17
	s_cselect_b64 s[0:1], -1, 0
	s_cmp_gt_i32 s29, 16
	s_cselect_b64 s[2:3], -1, 0
	s_and_b64 s[0:1], s[0:1], s[2:3]
	s_andn2_b64 vcc, exec, s[0:1]
	s_cbranch_vccnz .LBB0_1542
	s_mov_b64 s[8:9], exec
	v_readlane_b32 s0, v254, 4
	v_lshrrev_b32_e32 v0, 6, v200
	s_lshl_b32 s3, s30, 3
	v_readfirstlane_b32 s2, v0
	v_mbcnt_lo_u32_b32 v0, -1, 0
	v_mbcnt_hi_u32_b32 v0, -1, v0
	s_add_i32 s2, s2, s0
	s_cmp_ge_i32 s2, 0x10000
	s_cbranch_scc1 .Llnb1_done
	v_lshlrev_b32_e32 v1, 3, v0
	v_lshlrev_b32_e32 v0, 4, v0
	s_add_u32 s4, s36, 4096
	s_addc_u32 s5, s37, 0
	s_add_u32 s6, s38, 4096
	s_addc_u32 s7, s39, 0
	global_load_dwordx4 v[80:83], v0, s[4:5] offset:0
	global_load_dwordx4 v[84:87], v0, s[4:5] offset:1024
	global_load_dwordx4 v[88:91], v0, s[4:5] offset:2048
	global_load_dwordx4 v[92:95], v0, s[4:5] offset:3072
	global_load_dwordx4 v[96:99], v0, s[6:7] offset:0
	global_load_dwordx4 v[100:103], v0, s[6:7] offset:1024
	global_load_dwordx4 v[104:107], v0, s[6:7] offset:2048
	global_load_dwordx4 v[108:111], v0, s[6:7] offset:3072
	s_add_u32 s10, s26, 0x6000000
	s_addc_u32 s11, s27, 0
	v_mov_b32_e32 v112, 0x3727c5ac
	s_add_i32 s12, s2, s3
	s_cmp_lt_i32 s12, 0x10000
	s_cselect_b32 s13, s12, s2
	s_sub_i32 s4, 0xffff, s2
	s_lshl_b32 s4, s4, 12
	s_add_u32 s4, s24, s4
	s_addc_u32 s5, s25, 0
	s_sub_i32 s6, 0xffff, s13
	s_lshl_b32 s6, s6, 12
	s_add_u32 s6, s24, s6
	s_addc_u32 s7, s25, 0
	global_load_dwordx4 v[48:51], v0, s[4:5] offset:0
	global_load_dwordx4 v[52:55], v0, s[4:5] offset:1024
	global_load_dwordx4 v[56:59], v0, s[4:5] offset:2048
	global_load_dwordx4 v[60:63], v0, s[4:5] offset:3072
	global_load_dwordx4 v[64:67], v0, s[6:7] offset:0
	global_load_dwordx4 v[68:71], v0, s[6:7] offset:1024
	global_load_dwordx4 v[72:75], v0, s[6:7] offset:2048
	global_load_dwordx4 v[76:79], v0, s[6:7] offset:3072
	s_waitcnt vmcnt(0)
	s_branch .Llnb1_enter

.LBB0_1765:
	s_cmp_lt_i32 s28, 21
	s_cselect_b64 s[0:1], -1, 0
	s_cmp_gt_i32 s29, 20
	s_cselect_b64 s[2:3], -1, 0
	s_and_b64 s[0:1], s[0:1], s[2:3]
	s_andn2_b64 vcc, exec, s[0:1]
	s_cbranch_vccnz .LBB0_1833
	s_mov_b64 s[10:11], exec
	v_readlane_b32 s0, v254, 4
	v_lshrrev_b32_e32 v0, 6, v200
	s_lshl_b32 s3, s30, 3
	v_readfirstlane_b32 s2, v0
	v_mbcnt_lo_u32_b32 v0, -1, 0
	v_mbcnt_hi_u32_b32 v0, -1, v0
	s_add_i32 s2, s2, s0
	s_cmp_ge_i32 s2, 0x10000
	s_cbranch_scc1 .Llnb2_done
	v_lshlrev_b32_e32 v1, 3, v0
	v_lshlrev_b32_e32 v0, 4, v0
	s_add_u32 s4, s40, 4096
	s_addc_u32 s5, s41, 0
	s_add_u32 s6, s42, 4096
	s_addc_u32 s7, s43, 0
	global_load_dwordx4 v[80:83], v0, s[4:5] offset:0
	global_load_dwordx4 v[84:87], v0, s[4:5] offset:1024
	global_load_dwordx4 v[88:91], v0, s[4:5] offset:2048
	global_load_dwordx4 v[92:95], v0, s[4:5] offset:3072
	global_load_dwordx4 v[96:99], v0, s[6:7] offset:0
	global_load_dwordx4 v[100:103], v0, s[6:7] offset:1024
	global_load_dwordx4 v[104:107], v0, s[6:7] offset:2048
	global_load_dwordx4 v[108:111], v0, s[6:7] offset:3072
	v_mov_b32_e32 v112, 0x3727c5ac
	s_add_i32 s12, s2, s3
	s_cmp_lt_i32 s12, 0x10000
	s_cselect_b32 s13, s12, s2
	s_sub_i32 s4, 0xffff, s2
	s_lshl_b32 s4, s4, 12
	s_add_u32 s4, s24, s4
	s_addc_u32 s5, s25, 0
	s_sub_i32 s6, 0xffff, s13
	s_lshl_b32 s6, s6, 12
	s_add_u32 s6, s24, s6
	s_addc_u32 s7, s25, 0
	global_load_dwordx4 v[48:51], v0, s[4:5] offset:0
	global_load_dwordx4 v[52:55], v0, s[4:5] offset:1024
	global_load_dwordx4 v[56:59], v0, s[4:5] offset:2048
	global_load_dwordx4 v[60:63], v0, s[4:5] offset:3072
	global_load_dwordx4 v[64:67], v0, s[6:7] offset:0
	global_load_dwordx4 v[68:71], v0, s[6:7] offset:1024
	global_load_dwordx4 v[72:75], v0, s[6:7] offset:2048
	global_load_dwordx4 v[76:79], v0, s[6:7] offset:3072
	s_waitcnt vmcnt(0)
	s_branch .Llnb2_enter

.Llnb2_nopf:
	v_add_f32_e32 v113, v16, v20
	v_add_f32_e32 v114, v17, v21
	v_add_f32_e32 v115, v18, v22
	v_add_f32_e32 v116, v19, v23
	v_add_f32_e32 v117, v32, v36
	v_add_f32_e32 v118, v33, v37
	v_add_f32_e32 v119, v34, v38
	v_add_f32_e32 v120, v35, v39
	v_add_f32_e32 v113, v113, v24
	v_add_f32_e32 v113, v113, v28
	v_add_f32_e32 v114, v114, v25
	v_add_f32_e32 v114, v114, v29
	v_add_f32_e32 v115, v115, v26
	v_add_f32_e32 v115, v115, v30
	v_add_f32_e32 v116, v116, v27
	v_add_f32_e32 v116, v116, v31
	v_add_f32_e32 v117, v117, v40
	v_add_f32_e32 v117, v117, v44
	v_add_f32_e32 v118, v118, v41
	v_add_f32_e32 v118, v118, v45
	v_add_f32_e32 v119, v119, v42
	v_add_f32_e32 v119, v119, v46
	v_add_f32_e32 v120, v120, v43
	v_add_f32_e32 v120, v120, v47
	v_add_f32_e32 v113, v113, v114
	v_add_f32_e32 v115, v115, v116
	v_add_f32_e32 v117, v117, v118
	v_add_f32_e32 v119, v119, v120
	v_add_f32_e32 v113, v113, v115
	v_add_f32_e32 v117, v117, v119
	s_nop 1
	v_add_f32_dpp v113, v113, v113 quad_perm:[1,0,3,2] row_mask:0xf bank_mask:0xf
	v_add_f32_dpp v117, v117, v117 quad_perm:[1,0,3,2] row_mask:0xf bank_mask:0xf
	s_nop 1
	v_add_f32_dpp v113, v113, v113 quad_perm:[2,3,0,1] row_mask:0xf bank_mask:0xf
	v_add_f32_dpp v117, v117, v117 quad_perm:[2,3,0,1] row_mask:0xf bank_mask:0xf
	s_nop 1
	v_add_f32_dpp v113, v113, v113 row_half_mirror row_mask:0xf bank_mask:0xf
	v_add_f32_dpp v117, v117, v117 row_half_mirror row_mask:0xf bank_mask:0xf
	s_nop 1
	v_add_f32_dpp v113, v113, v113 row_mirror row_mask:0xf bank_mask:0xf
	v_add_f32_dpp v117, v117, v117 row_mirror row_mask:0xf bank_mask:0xf
	s_nop 1
	v_readlane_b32 s4, v113, 0
	v_readlane_b32 s5, v113, 16
	v_readlane_b32 s6, v113, 32
	v_readlane_b32 s7, v113, 48
	v_readlane_b32 s12, v117, 0
	v_readlane_b32 s13, v117, 16
	v_readlane_b32 s0, v117, 32
	v_readlane_b32 s1, v117, 48
	s_nop 1
	v_mov_b32_e32 v113, s4
	v_mov_b32_e32 v117, s12
	v_add_f32_e32 v113, s5, v113
	v_add_f32_e32 v117, s13, v117
	v_add_f32_e32 v113, s6, v113
	v_add_f32_e32 v117, s0, v117
	v_add_f32_e32 v113, s7, v113
	v_add_f32_e32 v117, s1, v117
	v_fmamk_f32 v16, v113, 0xba800000, v16
	v_fmamk_f32 v17, v113, 0xba800000, v17
	v_fmamk_f32 v18, v113, 0xba800000, v18
	v_fmamk_f32 v19, v113, 0xba800000, v19
	v_fmamk_f32 v20, v113, 0xba800000, v20
	v_fmamk_f32 v21, v113, 0xba800000, v21
	v_fmamk_f32 v22, v113, 0xba800000, v22
	v_fmamk_f32 v23, v113, 0xba800000, v23
	v_fmamk_f32 v24, v113, 0xba800000, v24
	v_fmamk_f32 v25, v113, 0xba800000, v25
	v_fmamk_f32 v26, v113, 0xba800000, v26
	v_fmamk_f32 v27, v113, 0xba800000, v27
	v_fmamk_f32 v28, v113, 0xba800000, v28
	v_fmamk_f32 v29, v113, 0xba800000, v29
	v_fmamk_f32 v30, v113, 0xba800000, v30
	v_fmamk_f32 v31, v113, 0xba800000, v31
	v_fmamk_f32 v32, v117, 0xba800000, v32
	v_fmamk_f32 v33, v117, 0xba800000, v33
	v_fmamk_f32 v34, v117, 0xba800000, v34
	v_fmamk_f32 v35, v117, 0xba800000, v35
	v_fmamk_f32 v36, v117, 0xba800000, v36
	v_fmamk_f32 v37, v117, 0xba800000, v37
	v_fmamk_f32 v38, v117, 0xba800000, v38
	v_fmamk_f32 v39, v117, 0xba800000, v39
	v_fmamk_f32 v40, v117, 0xba800000, v40
	v_fmamk_f32 v41, v117, 0xba800000, v41
	v_fmamk_f32 v42, v117, 0xba800000, v42
	v_fmamk_f32 v43, v117, 0xba800000, v43
	v_fmamk_f32 v44, v117, 0xba800000, v44
	v_fmamk_f32 v45, v117, 0xba800000, v45
	v_fmamk_f32 v46, v117, 0xba800000, v46
	v_fmamk_f32 v47, v117, 0xba800000, v47
	v_mul_f32_e32 v113, v16, v16
	v_mul_f32_e32 v114, v17, v17
	v_mul_f32_e32 v115, v18, v18
	v_mul_f32_e32 v116, v19, v19
	v_mul_f32_e32 v117, v32, v32
	v_mul_f32_e32 v118, v33, v33
	v_mul_f32_e32 v119, v34, v34
	v_mul_f32_e32 v120, v35, v35
	v_fmac_f32_e32 v113, v20, v20
	v_fmac_f32_e32 v113, v24, v24
	v_fmac_f32_e32 v113, v28, v28
	v_fmac_f32_e32 v114, v21, v21
	v_fmac_f32_e32 v114, v25, v25
	v_fmac_f32_e32 v114, v29, v29
	v_fmac_f32_e32 v115, v22, v22
	v_fmac_f32_e32 v115, v26, v26
	v_fmac_f32_e32 v115, v30, v30
	v_fmac_f32_e32 v116, v23, v23
	v_fmac_f32_e32 v116, v27, v27
	v_fmac_f32_e32 v116, v31, v31
	v_fmac_f32_e32 v117, v36, v36
	v_fmac_f32_e32 v117, v40, v40
	v_fmac_f32_e32 v117, v44, v44
	v_fmac_f32_e32 v118, v37, v37
	v_fmac_f32_e32 v118, v41, v41
	v_fmac_f32_e32 v118, v45, v45
	v_fmac_f32_e32 v119, v38, v38
	v_fmac_f32_e32 v119, v42, v42
	v_fmac_f32_e32 v119, v46, v46
	v_fmac_f32_e32 v120, v39, v39
	v_fmac_f32_e32 v120, v43, v43
	v_fmac_f32_e32 v120, v47, v47
	v_add_f32_e32 v113, v113, v114
	v_add_f32_e32 v115, v115, v116
	v_add_f32_e32 v117, v117, v118
	v_add_f32_e32 v119, v119, v120
	v_add_f32_e32 v113, v113, v115
	v_add_f32_e32 v117, v117, v119
	s_nop 1
	v_add_f32_dpp v113, v113, v113 quad_perm:[1,0,3,2] row_mask:0xf bank_mask:0xf
	v_add_f32_dpp v117, v117, v117 quad_perm:[1,0,3,2] row_mask:0xf bank_mask:0xf
	s_nop 1
	v_add_f32_dpp v113, v113, v113 quad_perm:[2,3,0,1] row_mask:0xf bank_mask:0xf
	v_add_f32_dpp v117, v117, v117 quad_perm:[2,3,0,1] row_mask:0xf bank_mask:0xf
	s_nop 1
	v_add_f32_dpp v113, v113, v113 row_half_mirror row_mask:0xf bank_mask:0xf
	v_add_f32_dpp v117, v117, v117 row_half_mirror row_mask:0xf bank_mask:0xf
	s_nop 1
	v_add_f32_dpp v113, v113, v113 row_mirror row_mask:0xf bank_mask:0xf
	v_add_f32_dpp v117, v117, v117 row_mirror row_mask:0xf bank_mask:0xf
	s_nop 1
	v_readlane_b32 s4, v113, 0
	v_readlane_b32 s5, v113, 16
	v_readlane_b32 s6, v113, 32
	v_readlane_b32 s7, v113, 48
	v_readlane_b32 s12, v117, 0
	v_readlane_b32 s13, v117, 16
	v_readlane_b32 s0, v117, 32
	v_readlane_b32 s1, v117, 48
	s_nop 1
	v_mov_b32_e32 v113, s4
	v_mov_b32_e32 v117, s12
	v_add_f32_e32 v113, s5, v113
	v_add_f32_e32 v117, s13, v117
	v_add_f32_e32 v113, s6, v113
	v_add_f32_e32 v117, s0, v117
	v_add_f32_e32 v113, s7, v113
	v_add_f32_e32 v117, s1, v117
	v_fmamk_f32 v113, v113, 0x3a800000, v112
	v_fmamk_f32 v117, v117, 0x3a800000, v112
	v_rsq_f32_e32 v113, v113
	v_rsq_f32_e32 v117, v117
	s_nop 0
	v_mul_f32_e32 v16, v16, v113
	v_mul_f32_e32 v17, v17, v113
	v_mul_f32_e32 v18, v18, v113
	v_mul_f32_e32 v19, v19, v113
	v_mul_f32_e32 v20, v20, v113
	v_mul_f32_e32 v21, v21, v113
	v_mul_f32_e32 v22, v22, v113
	v_mul_f32_e32 v23, v23, v113
	v_mul_f32_e32 v24, v24, v113
	v_mul_f32_e32 v25, v25, v113
	v_mul_f32_e32 v26, v26, v113
	v_mul_f32_e32 v27, v27, v113
	v_mul_f32_e32 v28, v28, v113
	v_mul_f32_e32 v29, v29, v113
	v_mul_f32_e32 v30, v30, v113
	v_mul_f32_e32 v31, v31, v113
	v_fma_f32 v16, v16, v80, v96
	v_fma_f32 v17, v17, v81, v97
	v_fma_f32 v18, v18, v82, v98
	v_fma_f32 v19, v19, v83, v99
	v_fma_f32 v20, v20, v84, v100
	v_fma_f32 v21, v21, v85, v101
	v_fma_f32 v22, v22, v86, v102
	v_fma_f32 v23, v23, v87, v103
	v_fma_f32 v24, v24, v88, v104
	v_fma_f32 v25, v25, v89, v105
	v_fma_f32 v26, v26, v90, v106
	v_fma_f32 v27, v27, v91, v107
	v_fma_f32 v28, v28, v92, v108
	v_fma_f32 v29, v29, v93, v109
	v_fma_f32 v30, v30, v94, v110
	v_fma_f32 v31, v31, v95, v111
	v_mul_f32_e32 v32, v32, v117
	v_mul_f32_e32 v33, v33, v117
	v_mul_f32_e32 v34, v34, v117
	v_mul_f32_e32 v35, v35, v117
	v_mul_f32_e32 v36, v36, v117
	v_mul_f32_e32 v37, v37, v117
	v_mul_f32_e32 v38, v38, v117
	v_mul_f32_e32 v39, v39, v117
	v_mul_f32_e32 v40, v40, v117
	v_mul_f32_e32 v41, v41, v117
	v_mul_f32_e32 v42, v42, v117
	v_mul_f32_e32 v43, v43, v117
	v_mul_f32_e32 v44, v44, v117
	v_mul_f32_e32 v45, v45, v117
	v_mul_f32_e32 v46, v46, v117
	v_mul_f32_e32 v47, v47, v117
	v_fma_f32 v32, v32, v80, v96
	v_fma_f32 v33, v33, v81, v97
	v_fma_f32 v34, v34, v82, v98
	v_fma_f32 v35, v35, v83, v99
	v_fma_f32 v36, v36, v84, v100
	v_fma_f32 v37, v37, v85, v101
	v_fma_f32 v38, v38, v86, v102
	v_fma_f32 v39, v39, v87, v103
	v_fma_f32 v40, v40, v88, v104
	v_fma_f32 v41, v41, v89, v105
	v_fma_f32 v42, v42, v90, v106
	v_fma_f32 v43, v43, v91, v107
	v_fma_f32 v44, v44, v92, v108
	v_fma_f32 v45, v45, v93, v109
	v_fma_f32 v46, v46, v94, v110
	v_fma_f32 v47, v47, v95, v111
	s_sub_i32 s4, 0xffff, s8
	s_lshl_b32 s4, s4, 12
	s_add_u32 s4, s24, s4
	s_addc_u32 s5, s25, 0
	global_store_dwordx4 v0, v[16:19], s[4:5] offset:0
	global_store_dwordx4 v0, v[20:23], s[4:5] offset:1024
	global_store_dwordx4 v0, v[24:27], s[4:5] offset:2048
	global_store_dwordx4 v0, v[28:31], s[4:5] offset:3072
	s_cmp_ge_i32 s9, 0x10000
	s_cbranch_scc1 .Llnb2_st1
	s_sub_i32 s6, 0xffff, s9
	s_lshl_b32 s6, s6, 12
	s_add_u32 s6, s24, s6
	s_addc_u32 s7, s25, 0
	global_store_dwordx4 v0, v[32:35], s[6:7] offset:0
	global_store_dwordx4 v0, v[36:39], s[6:7] offset:1024
	global_store_dwordx4 v0, v[40:43], s[6:7] offset:2048
	global_store_dwordx4 v0, v[44:47], s[6:7] offset:3072
